# attention item prologue: rope-Q fragment loads issued with the first Q batch (one round trip fewer)
# baseline (speedup 1.0000x reference)
.LBB0_2188:
	s_ashr_i32 s5, s14, 31
	s_lshr_b32 s5, s5, 30
	s_add_i32 s5, s14, s5
	s_and_b32 s5, s5, -4
	s_sub_i32 s34, s14, s5
	s_ashr_i32 s75, s74, 31
	s_mul_i32 s8, s74, 0x600
	s_mul_hi_i32 s5, s74, 0x600
	s_add_u32 s8, s66, s8
	s_mul_i32 s14, s34, 0xc0
	s_addc_u32 s5, s67, s5
	s_ashr_i32 s15, s14, 31
	s_lshl_b64 s[14:15], s[14:15], 1
	s_add_u32 s14, s8, s14
	v_ashrrev_i32_e32 v138, 6, v162
	s_addc_u32 s15, s5, s15
	v_and_b32_e32 v170, 31, v199
	v_lshlrev_b32_e32 v136, 5, v138
	v_bfe_u32 v171, v199, 5, 1
	v_or_b32_e32 v16, v136, v170
	v_mov_b64_e32 v[0:1], s[14:15]
	s_movk_i32 s5, 0x600
	v_and_b32_e32 v141, 63, v199
	v_lshlrev_b32_e32 v172, 13, v138
	v_mad_i64_i32 v[0:1], s[14:15], v16, s5, v[0:1]
	v_lshlrev_b32_e32 v160, 4, v171
	v_lshlrev_b32_e32 v140, 4, v141
	v_lshl_add_u64 v[18:19], v[0:1], 0, v[160:161]
	v_add_u32_e32 v0, s73, v172
	global_load_dwordx4 v[108:111], v[18:19], off
	global_load_dwordx4 v[104:107], v[18:19], off offset:32
	global_load_dwordx4 v[100:103], v[18:19], off offset:64
	global_load_dwordx4 v[96:99], v[18:19], off offset:96
	v_add_u32_e32 v139, v0, v140
	global_load_dwordx4 v[0:3], v[18:19], off offset:224
	global_load_dwordx4 v[4:7], v[18:19], off offset:192
	global_load_dwordx4 v[8:11], v[18:19], off offset:160
	global_load_dwordx4 v[12:15], v[18:19], off offset:128
	global_load_dwordx4 v[20:23], v[18:19], off offset:256
	global_load_dwordx4 v[24:27], v[18:19], off offset:288
	global_load_dwordx4 v[28:31], v[18:19], off offset:320
	global_load_dwordx4 v[32:35], v[18:19], off offset:352
	s_cmp_lt_i32 s13, 0
	s_waitcnt vmcnt(0)
	ds_write_b128 v139, v[12:15]
	ds_write_b128 v139, v[8:11] offset:1024
	ds_write_b128 v139, v[4:7] offset:2048
	ds_write_b128 v139, v[0:3] offset:3072
	s_nop 3
	v_mov_b64_e32 v[12:13], v[24:25]
	v_mov_b64_e32 v[14:15], v[26:27]
	v_mov_b64_e32 v[8:9], v[32:33]
	v_mov_b64_e32 v[10:11], v[34:35]
	v_mov_b64_e32 v[4:5], v[20:21]
	v_mov_b64_e32 v[6:7], v[22:23]
	v_mov_b64_e32 v[0:1], v[28:29]
	v_mov_b64_e32 v[2:3], v[30:31]
	s_cbranch_scc1 .LBB0_2190
	v_add_u32_e32 v16, s13, v16
	v_lshlrev_b32_e32 v38, 3, v171
	v_ashrrev_i32_e32 v17, 6, v16
	v_cvt_f32_i32_e32 v39, v17
	v_cvt_f32_ubyte0_e32 v17, v38
	v_mul_f32_e32 v17, 0xbf549a78, v17
	v_exp_f32_e32 v17, v17
	v_or_b32_e32 v19, 1, v38
	v_cvt_f32_ubyte0_e32 v19, v19
	v_and_b32_e32 v16, 63, v16
	v_mul_f32_e32 v19, 0xbf549a78, v19
	v_cvt_f32_ubyte0_e32 v41, v16
	v_exp_f32_e32 v23, v19
	v_mul_f32_e32 v16, v17, v39
	v_mul_f32_e32 v17, v17, v41
	v_mul_f32_e32 v17, 0.15915494, v17
	v_fract_f32_e32 v17, v17
	v_cos_f32_e32 v22, v17
	v_sin_f32_e32 v24, v17
	v_mul_f32_e32 v17, v23, v39
	v_mul_f32_e32 v16, 0.15915494, v16
	v_mul_f32_e32 v17, 0.15915494, v17
	v_fract_f32_e32 v18, v16
	v_fract_f32_e32 v19, v17
	v_cos_f32_e32 v16, v18
	v_cos_f32_e32 v17, v19
	v_sin_f32_e32 v18, v18
	v_sin_f32_e32 v19, v19
	s_waitcnt vmcnt(2)
	v_and_b32_e32 v29, 0xffff0000, v12
	v_lshlrev_b32_e32 v28, 16, v12
	v_and_b32_e32 v27, 0xffff0000, v4
	v_lshlrev_b32_e32 v26, 16, v4
	v_pk_mul_f32 v[20:21], v[16:17], v[28:29]
	v_mul_f32_e32 v4, v23, v41
	v_pk_fma_f32 v[20:21], v[18:19], v[26:27], v[20:21]
	v_pk_mul_f32 v[18:19], v[18:19], v[28:29]
	v_mul_f32_e32 v4, 0.15915494, v4
	v_pk_fma_f32 v[26:27], v[16:17], v[26:27], v[18:19] neg_lo:[0,0,1] neg_hi:[0,0,1]
	s_waitcnt vmcnt(1)
	v_and_b32_e32 v19, 0xffff0000, v0
	v_lshlrev_b32_e32 v18, 16, v0
	v_or_b32_e32 v0, 2, v38
	v_cvt_f32_ubyte0_e32 v0, v0
	v_mul_f32_e32 v0, 0xbf549a78, v0
	v_fract_f32_e32 v4, v4
	v_exp_f32_e32 v0, v0
	v_cos_f32_e32 v23, v4
	v_sin_f32_e32 v25, v4
	s_waitcnt vmcnt(0)
	v_and_b32_e32 v29, 0xffff0000, v8
	v_lshlrev_b32_e32 v28, 16, v8
	v_mul_f32_e32 v4, v0, v39
	v_pk_mul_f32 v[16:17], v[22:23], v[28:29]
	v_mul_f32_e32 v4, 0.15915494, v4
	v_pk_fma_f32 v[16:17], v[24:25], v[18:19], v[16:17]
	v_pk_mul_f32 v[24:25], v[24:25], v[28:29]
	v_fract_f32_e32 v4, v4
	v_pk_fma_f32 v[18:19], v[22:23], v[18:19], v[24:25] neg_lo:[0,0,1] neg_hi:[0,0,1]
	v_cos_f32_e32 v22, v4
	v_sin_f32_e32 v24, v4
	v_or_b32_e32 v4, 3, v38
	v_cvt_f32_ubyte0_e32 v4, v4
	v_mul_f32_e32 v4, 0xbf549a78, v4
	v_exp_f32_e32 v8, v4
	v_mul_f32_e32 v0, v0, v41
	v_mul_f32_e32 v0, 0.15915494, v0
	v_fract_f32_e32 v0, v0
	v_cos_f32_e32 v4, v0
	v_sin_f32_e32 v12, v0
	v_mul_f32_e32 v0, v8, v39
	v_mul_f32_e32 v0, 0.15915494, v0
	v_fract_f32_e32 v0, v0
	v_cos_f32_e32 v23, v0
	v_sin_f32_e32 v25, v0
	v_and_b32_e32 v31, 0xffff0000, v13
	v_lshlrev_b32_e32 v30, 16, v13
	v_and_b32_e32 v29, 0xffff0000, v5
	v_lshlrev_b32_e32 v28, 16, v5
	v_pk_mul_f32 v[32:33], v[22:23], v[30:31]
	v_mul_f32_e32 v0, v8, v41
	v_pk_fma_f32 v[32:33], v[24:25], v[28:29], v[32:33]
	v_pk_mul_f32 v[24:25], v[24:25], v[30:31]
	v_mul_f32_e32 v0, 0.15915494, v0
	v_pk_fma_f32 v[22:23], v[22:23], v[28:29], v[24:25] neg_lo:[0,0,1] neg_hi:[0,0,1]
	v_fract_f32_e32 v0, v0
	v_or_b32_e32 v28, 4, v38
	v_cos_f32_e32 v5, v0
	v_cvt_f32_ubyte0_e32 v28, v28
	v_sin_f32_e32 v13, v0
	v_mul_f32_e32 v28, 0xbf549a78, v28
	v_exp_f32_e32 v28, v28
	v_and_b32_e32 v25, 0xffff0000, v1
	v_lshlrev_b32_e32 v24, 16, v1
	v_and_b32_e32 v1, 0xffff0000, v9
	v_lshlrev_b32_e32 v0, 16, v9
	v_pk_mul_f32 v[8:9], v[4:5], v[0:1]
	v_pk_mul_f32 v[0:1], v[12:13], v[0:1]
	v_pk_fma_f32 v[8:9], v[12:13], v[24:25], v[8:9]
	v_or_b32_e32 v13, 5, v38
	v_pk_fma_f32 v[0:1], v[4:5], v[24:25], v[0:1] neg_lo:[0,0,1] neg_hi:[0,0,1]
	v_mul_f32_e32 v4, v28, v39
	v_cvt_f32_ubyte0_e32 v13, v13
	v_mul_f32_e32 v4, 0.15915494, v4
	v_mul_f32_e32 v13, 0xbf549a78, v13
	v_fract_f32_e32 v5, v4
	v_exp_f32_e32 v25, v13
	v_cos_f32_e32 v4, v5
	v_sin_f32_e32 v12, v5
	v_mul_f32_e32 v5, v28, v41
	v_mul_f32_e32 v5, 0.15915494, v5
	v_fract_f32_e32 v5, v5
	v_cos_f32_e32 v24, v5
	v_sin_f32_e32 v28, v5
	v_mul_f32_e32 v5, v25, v39
	v_mul_f32_e32 v5, 0.15915494, v5
	v_fract_f32_e32 v13, v5
	v_cos_f32_e32 v5, v13
	v_sin_f32_e32 v13, v13
	v_and_b32_e32 v35, 0xffff0000, v14
	v_lshlrev_b32_e32 v34, 16, v14
	v_and_b32_e32 v31, 0xffff0000, v6
	v_lshlrev_b32_e32 v30, 16, v6
	v_pk_mul_f32 v[36:37], v[4:5], v[34:35]
	v_mul_f32_e32 v6, v25, v41
	v_pk_fma_f32 v[36:37], v[12:13], v[30:31], v[36:37]
	v_pk_mul_f32 v[12:13], v[12:13], v[34:35]
	v_mul_f32_e32 v6, 0.15915494, v6
	v_pk_fma_f32 v[4:5], v[4:5], v[30:31], v[12:13] neg_lo:[0,0,1] neg_hi:[0,0,1]
	v_and_b32_e32 v13, 0xffff0000, v2
	v_lshlrev_b32_e32 v12, 16, v2
	v_or_b32_e32 v2, 6, v38
	v_cvt_f32_ubyte0_e32 v2, v2
	v_mul_f32_e32 v2, 0xbf549a78, v2
	v_fract_f32_e32 v6, v6
	v_exp_f32_e32 v2, v2
	v_cos_f32_e32 v25, v6
	v_sin_f32_e32 v29, v6
	v_and_b32_e32 v31, 0xffff0000, v10
	v_lshlrev_b32_e32 v30, 16, v10
	v_mul_f32_e32 v6, v2, v39
	v_pk_mul_f32 v[34:35], v[24:25], v[30:31]
	v_mul_f32_e32 v6, 0.15915494, v6
	v_pk_fma_f32 v[34:35], v[28:29], v[12:13], v[34:35]
	v_pk_mul_f32 v[28:29], v[28:29], v[30:31]
	v_fract_f32_e32 v6, v6
	v_pk_fma_f32 v[24:25], v[24:25], v[12:13], v[28:29] neg_lo:[0,0,1] neg_hi:[0,0,1]
	v_cos_f32_e32 v10, v6
	v_sin_f32_e32 v13, v6
	v_mul_f32_e32 v2, v2, v41
	v_mul_f32_e32 v2, 0.15915494, v2
	v_lshlrev_b32_e32 v28, 16, v7
	v_lshlrev_b32_e32 v14, 16, v15
	v_fract_f32_e32 v2, v2
	v_mul_f32_e32 v6, v10, v28
	v_mul_f32_e32 v12, v13, v14
	v_mul_f32_e32 v28, v13, v28
	v_cos_f32_e32 v13, v2
	v_sin_f32_e32 v29, v2
	v_or_b32_e32 v2, 7, v38
	v_cvt_f32_ubyte0_e32 v2, v2
	v_mul_f32_e32 v2, 0xbf549a78, v2
	v_exp_f32_e32 v46, v2
	v_lshlrev_b32_e32 v31, 16, v3
	v_lshlrev_b32_e32 v30, 16, v11
	v_mul_f32_e32 v14, v10, v14
	v_mul_f32_e32 v2, v13, v31
	v_mul_f32_e32 v10, v29, v30
	v_mul_f32_e32 v30, v13, v30
	v_mul_f32_e32 v13, v46, v39
	v_mul_f32_e32 v13, 0.15915494, v13
	v_fract_f32_e32 v13, v13
	v_cos_f32_e32 v38, v13
	v_sin_f32_e32 v39, v13
	v_and_b32_e32 v43, 0xffff0000, v15
	v_and_b32_e32 v42, 0xffff0000, v7
	v_mul_f32_e32 v40, v29, v31
	v_pk_mul_f32 v[44:45], v[38:39], v[42:43]
	v_bfe_u32 v15, v23, 16, 1
	v_mov_b32_e32 v7, v44
	v_mov_b32_e32 v13, v45
	v_pk_add_f32 v[6:7], v[6:7], v[12:13] neg_lo:[0,1] neg_hi:[0,1]
	v_bfe_u32 v12, v5, 16, 1
	v_bfe_u32 v13, v4, 16, 1
	v_bfe_u32 v29, v22, 16, 1
	v_add3_u32 v4, v4, v13, s93
	v_add3_u32 v5, v5, v12, s93
	v_mov_b32_e32 v12, v39
	v_mov_b32_e32 v13, v38
	v_bfe_u32 v47, v6, 16, 1
	v_add3_u32 v22, v22, v29, s93
	v_add3_u32 v15, v23, v15, s93
	v_pk_mul_f32 v[12:13], v[12:13], v[42:43]
	v_add3_u32 v47, v6, v47, s93
	v_perm_b32 v6, v5, v4, s89
	v_perm_b32 v5, v15, v22, s89
	v_mov_b32_e32 v29, v12
	v_mov_b32_e32 v15, v13
	v_pk_add_f32 v[12:13], v[28:29], v[14:15]
	v_bfe_u32 v14, v37, 16, 1
	v_bfe_u32 v15, v36, 16, 1
	v_bfe_u32 v31, v27, 16, 1
	v_bfe_u32 v44, v26, 16, 1
	v_add3_u32 v15, v36, v15, s93
	v_add3_u32 v14, v37, v14, s93
	v_add3_u32 v26, v26, v44, s93
	v_add3_u32 v27, v27, v31, s93
	v_perm_b32 v14, v14, v15, s89
	v_mul_f32_e32 v15, v46, v41
	v_perm_b32 v4, v27, v26, s89
	v_bfe_u32 v22, v33, 16, 1
	v_bfe_u32 v23, v32, 16, 1
	v_bfe_u32 v26, v21, 16, 1
	v_bfe_u32 v27, v20, 16, 1
	v_bfe_u32 v28, v13, 16, 1
	v_bfe_u32 v29, v12, 16, 1
	v_mul_f32_e32 v15, 0.15915494, v15
	v_add3_u32 v29, v12, v29, s93
	v_add3_u32 v28, v13, v28, s93
	v_add3_u32 v12, v20, v27, s93
	v_add3_u32 v20, v21, v26, s93
	v_add3_u32 v13, v32, v23, s93
	v_add3_u32 v21, v33, v22, s93
	v_fract_f32_e32 v15, v15
	v_perm_b32 v13, v21, v13, s89
	v_perm_b32 v12, v20, v12, s89
	v_cos_f32_e32 v20, v15
	v_sin_f32_e32 v21, v15
	v_and_b32_e32 v23, 0xffff0000, v11
	v_and_b32_e32 v22, 0xffff0000, v3
	v_perm_b32 v15, v28, v29, s89
	v_pk_mul_f32 v[26:27], v[20:21], v[22:23]
	v_bfe_u32 v28, v19, 16, 1
	v_mov_b32_e32 v3, v26
	v_mov_b32_e32 v11, v27
	v_pk_add_f32 v[2:3], v[2:3], v[10:11] neg_lo:[0,1] neg_hi:[0,1]
	v_bfe_u32 v10, v25, 16, 1
	v_bfe_u32 v11, v24, 16, 1
	v_bfe_u32 v32, v2, 16, 1
	v_add3_u32 v32, v2, v32, s93
	v_add3_u32 v2, v24, v11, s93
	v_add3_u32 v10, v25, v10, s93
	v_perm_b32 v2, v10, v2, s89
	v_mov_b32_e32 v10, v21
	v_mov_b32_e32 v11, v20
	v_bfe_u32 v31, v3, 16, 1
	v_pk_mul_f32 v[10:11], v[10:11], v[22:23]
	v_bfe_u32 v26, v1, 16, 1
	v_bfe_u32 v27, v0, 16, 1
	v_bfe_u32 v29, v18, 16, 1
	v_add3_u32 v3, v3, v31, s93
	v_mov_b32_e32 v41, v10
	v_mov_b32_e32 v31, v11
	v_add3_u32 v18, v18, v29, s93
	v_add3_u32 v19, v19, v28, s93
	v_add3_u32 v0, v0, v27, s93
	v_add3_u32 v1, v1, v26, s93
	v_pk_add_f32 v[10:11], v[40:41], v[30:31]
	v_bfe_u32 v45, v7, 16, 1
	v_perm_b32 v1, v1, v0, s89
	v_perm_b32 v0, v19, v18, s89
	v_bfe_u32 v18, v35, 16, 1
	v_bfe_u32 v19, v34, 16, 1
	v_bfe_u32 v20, v9, 16, 1
	v_bfe_u32 v21, v8, 16, 1
	v_bfe_u32 v22, v17, 16, 1
	v_bfe_u32 v23, v16, 16, 1
	v_bfe_u32 v24, v11, 16, 1
	v_bfe_u32 v25, v10, 16, 1
	v_add3_u32 v7, v7, v45, s93
	v_add3_u32 v25, v10, v25, s93
	v_add3_u32 v11, v11, v24, s93
	v_add3_u32 v16, v16, v23, s93
	v_add3_u32 v17, v17, v22, s93
	v_add3_u32 v8, v8, v21, s93
	v_add3_u32 v9, v9, v20, s93
	v_add3_u32 v10, v34, v19, s93
	v_add3_u32 v18, v35, v18, s93
	v_perm_b32 v7, v7, v47, s89
	v_perm_b32 v3, v3, v32, s89
	v_perm_b32 v10, v18, v10, s89
	v_perm_b32 v9, v9, v8, s89
	v_perm_b32 v8, v17, v16, s89
	v_perm_b32 v11, v11, v25, s89
